# FoX tile body: PV MFMAs issued in the shadow of the next key-group's exp2/cvt (exp in place, packed row-sum); same accumulation order
# baseline (speedup 1.0000x reference)
; template <int MODE> ...
;     ...
;             float ps = 0.f;
; #pragma unroll
;             for (int r = 0; r < 16; ++r) { s0[r] = ex2(s0[r]); s1[r] = ex2(s1[r]); ps += s0[r] + s1[r]; }
;             l += ps;
;         } else {
; #pragma unroll
;             for (int r = 0; r < 16; ++r) { s0[r] = ex2(s0[r]) * linv; s1[r] = ex2(s1[r]) * linv; }
;             float quad[8], last[8], recv[8];
; #pragma unroll
;             for (int a = 0; a < 4; ++a) {
;                 quad[a] = (s0[4 * a] + s0[4 * a + 1]) + (s0[4 * a + 2] + s0[4 * a + 3]); last[a] = s0[4 * a + 3];
;                 quad[4 + a] = (s1[4 * a] + s1[4 * a + 1]) + (s1[4 * a + 2] + s1[4 * a + 3]); last[4 + a] = s1[4 * a + 3];
;             }
; #pragma unroll
;             for (int i = 0; i < 8; ++i) recv[i] = half_other(last[i], hl);
; #pragma unroll
;             for (int i = 0; i < 8; ++i) {
;                 const float prev = (i > 0) ? recv[i > 0 ? i - 1 : 0] : carry;
;                 float v = quad[i] + (hl ? recv[i] : prev);
;                 v += __shfl_xor(v, 1); v += __shfl_xor(v, 2);
;                 if ((n & 3) == 0) lds_st<float>(L + score_ofs + (16 * kt + 2 * i + hl) * 4, v);
;             }
;             carry = recv[7];
;         }
;         if (MODE != MODE_CMP1) {
;             bf16x8 pf[4];
; #pragma unroll
;             for (int ks = 0; ks < 4; ++ks) {
;                 const int hb = 8 * (ks & 1); u32x4 w;
;                 if (ks >> 1) { w.x = cvt_pk(s1[hb], s1[hb + 1]); w.y = cvt_pk(s1[hb + 2], s1[hb + 3]); w.z = cvt_pk(s1[hb + 4], s1[hb + 5]); w.w = cvt_pk(s1[hb + 6], s1[hb + 7]); }
;                 else { w.x = cvt_pk(s0[hb], s0[hb + 1]); w.y = cvt_pk(s0[hb + 2], s0[hb + 3]); w.z = cvt_pk(s0[hb + 4], s0[hb + 5]); w.w = cvt_pk(s0[hb + 6], s0[hb + 7]); }
;                 pf[ks] = __builtin_bit_cast(bf16x8, w);
;             }
;             const lptr vb_ = Vt + (4 * hl + q4) * VP + 32 * blk + 8 * p4;
; #pragma unroll
;             for (int c_ = 0; c_ < 2; ++c_)
; #pragma unroll
;                 for (int ks_ = 0; ks_ < 4; ++ks_) {
;                     const s16x4 lo_ = tr16(vb_ + (16 * ks_) * VP + 64 * c_), hi_ = tr16(vb_ + (16 * ks_ + 8) * VP + 64 * c_);
;                     const bf16x8 vf_ = {lo_[0], lo_[1], lo_[2], lo_[3], hi_[0], hi_[1], hi_[2], hi_[3]};
;                     o[c_] = mfma32(vf_, pf[ks_], o[c_]);
;                 }
.LBB0_182:
	s_waitcnt lgkmcnt(0)
	v_exp_f32_e32 v80, v80
	v_exp_f32_e32 v81, v81
	v_exp_f32_e32 v82, v82
	v_exp_f32_e32 v83, v83
	v_exp_f32_e32 v84, v84
	v_exp_f32_e32 v85, v85
	v_exp_f32_e32 v86, v86
	v_exp_f32_e32 v87, v87
	v_cvt_pk_bf16_f32 v170, v80, v81
	v_cvt_pk_bf16_f32 v171, v82, v83
	v_pk_add_f32 v[186:187], v[80:81], v[82:83]
	v_cvt_pk_bf16_f32 v172, v84, v85
	v_cvt_pk_bf16_f32 v173, v86, v87
	v_pk_add_f32 v[188:189], v[84:85], v[86:87]
	v_exp_f32_e32 v88, v88
	v_exp_f32_e32 v89, v89
	v_exp_f32_e32 v14, v14
	v_exp_f32_e32 v15, v15
	v_mfma_f32_32x32x16_bf16 v[16:31], v[206:209], v[170:173], v[16:31]
	v_exp_f32_e32 v12, v12
	v_exp_f32_e32 v13, v13
	v_exp_f32_e32 v10, v10
	v_exp_f32_e32 v11, v11
	v_mfma_f32_32x32x16_bf16 v[32:47], v[234:237], v[170:173], v[32:47]
	v_cvt_pk_bf16_f32 v174, v88, v89
	v_pk_add_f32 v[186:187], v[186:187], v[88:89]
	v_cvt_pk_bf16_f32 v175, v14, v15
	v_pk_add_f32 v[188:189], v[188:189], v[14:15]
	v_cvt_pk_bf16_f32 v176, v12, v13
	v_pk_add_f32 v[186:187], v[186:187], v[12:13]
	v_cvt_pk_bf16_f32 v177, v10, v11
	v_pk_add_f32 v[188:189], v[188:189], v[10:11]
	v_exp_f32_e32 v64, v64
	v_exp_f32_e32 v65, v65
	v_exp_f32_e32 v66, v66
	v_exp_f32_e32 v67, v67
	v_mfma_f32_32x32x16_bf16 v[16:31], v[210:213], v[174:177], v[16:31]
	v_exp_f32_e32 v68, v68
	v_exp_f32_e32 v69, v69
	v_exp_f32_e32 v70, v70
	v_exp_f32_e32 v71, v71
	v_mfma_f32_32x32x16_bf16 v[32:47], v[238:241], v[174:177], v[32:47]
	v_cvt_pk_bf16_f32 v178, v64, v65
	v_pk_add_f32 v[186:187], v[186:187], v[64:65]
	v_cvt_pk_bf16_f32 v179, v66, v67
	v_pk_add_f32 v[188:189], v[188:189], v[66:67]
	v_cvt_pk_bf16_f32 v180, v68, v69
	v_pk_add_f32 v[186:187], v[186:187], v[68:69]
	v_cvt_pk_bf16_f32 v181, v70, v71
	v_pk_add_f32 v[188:189], v[188:189], v[70:71]
	v_exp_f32_e32 v72, v72
	v_exp_f32_e32 v73, v73
	v_exp_f32_e32 v74, v74
	v_exp_f32_e32 v75, v75
	v_mfma_f32_32x32x16_bf16 v[16:31], v[226:229], v[178:181], v[16:31]
	v_exp_f32_e32 v76, v76
	v_exp_f32_e32 v77, v77
	v_exp_f32_e32 v78, v78
	v_exp_f32_e32 v79, v79
	v_mfma_f32_32x32x16_bf16 v[32:47], v[242:245], v[178:181], v[32:47]
	v_cvt_pk_bf16_f32 v182, v72, v73
	v_pk_add_f32 v[186:187], v[186:187], v[72:73]
	v_cvt_pk_bf16_f32 v183, v74, v75
	v_pk_add_f32 v[188:189], v[188:189], v[74:75]
	v_cvt_pk_bf16_f32 v184, v76, v77
	v_pk_add_f32 v[186:187], v[186:187], v[76:77]
	v_cvt_pk_bf16_f32 v185, v78, v79
	v_pk_add_f32 v[188:189], v[188:189], v[78:79]
	v_pk_add_f32 v[186:187], v[186:187], v[188:189]
	s_nop 0
	v_add_f32_e32 v186, v186, v187
	v_mfma_f32_32x32x16_bf16 v[16:31], v[230:233], v[182:185], v[16:31]
	v_add_f32_e32 v140, v140, v186
	v_mfma_f32_32x32x16_bf16 v[32:47], v[246:249], v[182:185], v[32:47]
	s_or_b64 exec, exec, s[56:57]
	s_cmp_lt_i32 s7, 0
	s_cbranch_scc1 .LBB0_186

; template <int MODE> ...
;     ...
;             float ps = 0.f;
; #pragma unroll
;             for (int r = 0; r < 16; ++r) { s0[r] = ex2(s0[r]); s1[r] = ex2(s1[r]); ps += s0[r] + s1[r]; }
;             l += ps;
;         } else {
; #pragma unroll
;             for (int r = 0; r < 16; ++r) { s0[r] = ex2(s0[r]) * linv; s1[r] = ex2(s1[r]) * linv; }
;             float quad[8], last[8], recv[8];
; #pragma unroll
;             for (int a = 0; a < 4; ++a) {
;                 quad[a] = (s0[4 * a] + s0[4 * a + 1]) + (s0[4 * a + 2] + s0[4 * a + 3]); last[a] = s0[4 * a + 3];
;                 quad[4 + a] = (s1[4 * a] + s1[4 * a + 1]) + (s1[4 * a + 2] + s1[4 * a + 3]); last[4 + a] = s1[4 * a + 3];
;             }
; #pragma unroll
;             for (int i = 0; i < 8; ++i) recv[i] = half_other(last[i], hl);
; #pragma unroll
;             for (int i = 0; i < 8; ++i) {
;                 const float prev = (i > 0) ? recv[i > 0 ? i - 1 : 0] : carry;
;                 float v = quad[i] + (hl ? recv[i] : prev);
;                 v += __shfl_xor(v, 1); v += __shfl_xor(v, 2);
;                 if ((n & 3) == 0) lds_st<float>(L + score_ofs + (16 * kt + 2 * i + hl) * 4, v);
;             }
;             carry = recv[7];
;         }
;         if (MODE != MODE_CMP1) {
;             bf16x8 pf[4];
; #pragma unroll
;             for (int ks = 0; ks < 4; ++ks) {
;                 const int hb = 8 * (ks & 1); u32x4 w;
;                 if (ks >> 1) { w.x = cvt_pk(s1[hb], s1[hb + 1]); w.y = cvt_pk(s1[hb + 2], s1[hb + 3]); w.z = cvt_pk(s1[hb + 4], s1[hb + 5]); w.w = cvt_pk(s1[hb + 6], s1[hb + 7]); }
;                 else { w.x = cvt_pk(s0[hb], s0[hb + 1]); w.y = cvt_pk(s0[hb + 2], s0[hb + 3]); w.z = cvt_pk(s0[hb + 4], s0[hb + 5]); w.w = cvt_pk(s0[hb + 6], s0[hb + 7]); }
;                 pf[ks] = __builtin_bit_cast(bf16x8, w);
;             }
;             const lptr vb_ = Vt + (4 * hl + q4) * VP + 32 * blk + 8 * p4;
; #pragma unroll
;             for (int c_ = 0; c_ < 2; ++c_)
; #pragma unroll
;                 for (int ks_ = 0; ks_ < 4; ++ks_) {
;                     const s16x4 lo_ = tr16(vb_ + (16 * ks_) * VP + 64 * c_), hi_ = tr16(vb_ + (16 * ks_ + 8) * VP + 64 * c_);
;                     const bf16x8 vf_ = {lo_[0], lo_[1], lo_[2], lo_[3], hi_[0], hi_[1], hi_[2], hi_[3]};
;                     o[c_] = mfma32(vf_, pf[ks_], o[c_]);
;                 }
.LBB0_198:
	s_waitcnt lgkmcnt(0)
	v_exp_f32_e32 v80, v80
	v_exp_f32_e32 v81, v81
	v_exp_f32_e32 v82, v82
	v_exp_f32_e32 v83, v83
	v_exp_f32_e32 v84, v84
	v_exp_f32_e32 v85, v85
	v_exp_f32_e32 v86, v86
	v_exp_f32_e32 v87, v87
	v_cvt_pk_bf16_f32 v170, v80, v81
	v_cvt_pk_bf16_f32 v171, v82, v83
	v_pk_add_f32 v[186:187], v[80:81], v[82:83]
	v_cvt_pk_bf16_f32 v172, v84, v85
	v_cvt_pk_bf16_f32 v173, v86, v87
	v_pk_add_f32 v[188:189], v[84:85], v[86:87]
	v_exp_f32_e32 v88, v88
	v_exp_f32_e32 v89, v89
	v_exp_f32_e32 v14, v14
	v_exp_f32_e32 v15, v15
	v_mfma_f32_32x32x16_bf16 v[16:31], v[206:209], v[170:173], v[16:31]
	v_exp_f32_e32 v12, v12
	v_exp_f32_e32 v13, v13
	v_exp_f32_e32 v10, v10
	v_exp_f32_e32 v11, v11
	v_mfma_f32_32x32x16_bf16 v[32:47], v[234:237], v[170:173], v[32:47]
	v_cvt_pk_bf16_f32 v174, v88, v89
	v_pk_add_f32 v[186:187], v[186:187], v[88:89]
	v_cvt_pk_bf16_f32 v175, v14, v15
	v_pk_add_f32 v[188:189], v[188:189], v[14:15]
	v_cvt_pk_bf16_f32 v176, v12, v13
	v_pk_add_f32 v[186:187], v[186:187], v[12:13]
	v_cvt_pk_bf16_f32 v177, v10, v11
	v_pk_add_f32 v[188:189], v[188:189], v[10:11]
	v_exp_f32_e32 v64, v64
	v_exp_f32_e32 v65, v65
	v_exp_f32_e32 v66, v66
	v_exp_f32_e32 v67, v67
	v_mfma_f32_32x32x16_bf16 v[16:31], v[210:213], v[174:177], v[16:31]
	v_exp_f32_e32 v68, v68
	v_exp_f32_e32 v69, v69
	v_exp_f32_e32 v70, v70
	v_exp_f32_e32 v71, v71
	v_mfma_f32_32x32x16_bf16 v[32:47], v[238:241], v[174:177], v[32:47]
	v_cvt_pk_bf16_f32 v178, v64, v65
	v_pk_add_f32 v[186:187], v[186:187], v[64:65]
	v_cvt_pk_bf16_f32 v179, v66, v67
	v_pk_add_f32 v[188:189], v[188:189], v[66:67]
	v_cvt_pk_bf16_f32 v180, v68, v69
	v_pk_add_f32 v[186:187], v[186:187], v[68:69]
	v_cvt_pk_bf16_f32 v181, v70, v71
	v_pk_add_f32 v[188:189], v[188:189], v[70:71]
	v_exp_f32_e32 v72, v72
	v_exp_f32_e32 v73, v73
	v_exp_f32_e32 v74, v74
	v_exp_f32_e32 v75, v75
	v_mfma_f32_32x32x16_bf16 v[16:31], v[226:229], v[178:181], v[16:31]
	v_exp_f32_e32 v76, v76
	v_exp_f32_e32 v77, v77
	v_exp_f32_e32 v78, v78
	v_exp_f32_e32 v79, v79
	v_mfma_f32_32x32x16_bf16 v[32:47], v[242:245], v[178:181], v[32:47]
	v_cvt_pk_bf16_f32 v182, v72, v73
	v_pk_add_f32 v[186:187], v[186:187], v[72:73]
	v_cvt_pk_bf16_f32 v183, v74, v75
	v_pk_add_f32 v[188:189], v[188:189], v[74:75]
	v_cvt_pk_bf16_f32 v184, v76, v77
	v_pk_add_f32 v[186:187], v[186:187], v[76:77]
	v_cvt_pk_bf16_f32 v185, v78, v79
	v_pk_add_f32 v[188:189], v[188:189], v[78:79]
	v_pk_add_f32 v[186:187], v[186:187], v[188:189]
	s_nop 0
	v_add_f32_e32 v186, v186, v187
	v_mfma_f32_32x32x16_bf16 v[16:31], v[230:233], v[182:185], v[16:31]
	v_add_f32_e32 v140, v140, v186
	v_mfma_f32_32x32x16_bf16 v[32:47], v[246:249], v[182:185], v[32:47]
	s_or_b64 exec, exec, s[58:59]
	s_andn2_b64 vcc, exec, s[50:51]
	s_cbranch_vccnz .LBB0_171
